# v23 + NA softmax row-max: the xor-32 ds_bpermute exchange replaced by v_permlane32_swap (one site per step)
# speedup vs baseline: 1.0020x; 1.0020x over previous
.LBB0_163:
	v_med3_i32 v137, s14, 4, 28
	s_cmp_lt_u32 s83, 14
	v_readfirstlane_b32 s14, v137
	s_cselect_b64 s[76:77], -1, 0
	s_add_i32 s19, s14, 0xfffc
	s_mul_i32 s33, s19, 57
	s_bfe_u32 s33, s33, 0x70009
	s_mul_i32 s33, s33, 9
	s_sub_i32 s19, s19, s33
	s_and_b32 s92, s19, 0xff
	v_lshl_add_u32 v138, s92, 13, v117
	v_add_u32_e32 v142, v138, v116
	v_add_u32_e32 v150, v138, v118
	ds_read_b128 v[138:141], v142
	ds_read_b128 v[142:145], v142 offset:2048
	ds_read_b128 v[146:149], v150
	ds_read_b128 v[150:153], v150 offset:2048
	v_med3_u32 v154, s22, 2, 26
	v_cmp_le_u32_e64 s[60:61], s18, v154
	s_and_b64 s[18:19], s[60:61], s[76:77]
	s_add_i32 s33, s14, 0xfffd
	s_and_b32 s76, s33, 0xff
	s_mul_i32 s76, s76, 57
	s_lshr_b32 s76, s76, 9
	s_mul_i32 s76, s76, 9
	s_sub_i32 s33, s33, s76
	s_and_b32 s91, s33, 0xff
	v_lshl_add_u32 v154, s91, 13, v117
	v_add_u32_e32 v158, v154, v116
	v_add_u32_e32 v166, v154, v118
	ds_read_b128 v[154:157], v158
	ds_read_b128 v[158:161], v158 offset:2048
	ds_read_b128 v[162:165], v166
	ds_read_b128 v[166:169], v166 offset:2048
	s_waitcnt vmcnt(11) lgkmcnt(7)
	v_mfma_f32_16x16x32_bf16 v[138:141], v[138:141], v[92:95], v[0:3]
	s_waitcnt lgkmcnt(6)
	v_mfma_f32_16x16x32_bf16 v[142:145], v[142:145], v[92:95], v[4:7]
	s_waitcnt vmcnt(10) lgkmcnt(5)
	v_mfma_f32_16x16x32_bf16 v[138:141], v[146:149], v[88:91], v[138:141]
	s_waitcnt lgkmcnt(4)
	v_mfma_f32_16x16x32_bf16 v[142:145], v[150:153], v[88:91], v[142:145]
	s_add_i32 s33, s14, 0xfffe
	s_and_b32 s76, s33, 0xff
	s_mul_i32 s76, s76, 57
	s_lshr_b32 s76, s76, 9
	s_mul_i32 s76, s76, 9
	s_sub_i32 s33, s33, s76
	s_and_b32 s90, s33, 0xff
	v_lshl_add_u32 v146, s90, 13, v117
	v_add_u32_e32 v150, v146, v116
	v_add_u32_e32 v174, v146, v118
	ds_read_b128 v[146:149], v150
	ds_read_b128 v[150:153], v150 offset:2048
	ds_read_b128 v[170:173], v174
	ds_read_b128 v[174:177], v174 offset:2048
	s_waitcnt lgkmcnt(7)
	v_mfma_f32_16x16x32_bf16 v[154:157], v[154:157], v[92:95], v[8:11]
	s_waitcnt lgkmcnt(6)
	v_mfma_f32_16x16x32_bf16 v[158:161], v[158:161], v[92:95], v[12:15]
	s_waitcnt lgkmcnt(5)
	v_mfma_f32_16x16x32_bf16 v[154:157], v[162:165], v[88:91], v[154:157]
	s_waitcnt lgkmcnt(4)
	v_mfma_f32_16x16x32_bf16 v[158:161], v[166:169], v[88:91], v[158:161]
	s_add_i32 s33, s14, 0xffff
	s_and_b32 s76, s33, 0xff
	s_mul_i32 s76, s76, 57
	s_lshr_b32 s76, s76, 9
	s_mul_i32 s76, s76, 9
	s_sub_i32 s33, s33, s76
	s_and_b32 s87, s33, 0xff
	v_lshl_add_u32 v162, s87, 13, v117
	v_add_u32_e32 v166, v162, v116
	v_add_u32_e32 v182, v162, v118
	ds_read_b128 v[162:165], v166
	ds_read_b128 v[166:169], v166 offset:2048
	ds_read_b128 v[178:181], v182
	ds_read_b128 v[182:185], v182 offset:2048
	s_waitcnt lgkmcnt(7)
	v_mfma_f32_16x16x32_bf16 v[146:149], v[146:149], v[92:95], v[16:19]
	s_waitcnt lgkmcnt(6)
	v_mfma_f32_16x16x32_bf16 v[150:153], v[150:153], v[92:95], v[20:23]
	s_waitcnt lgkmcnt(5)
	v_mfma_f32_16x16x32_bf16 v[146:149], v[170:173], v[88:91], v[146:149]
	s_waitcnt lgkmcnt(4)
	v_mfma_f32_16x16x32_bf16 v[150:153], v[174:177], v[88:91], v[150:153]
	v_mul_lo_u32 v170, v137, 29
	v_lshrrev_b32_e32 v170, 8, v170
	v_mul_lo_u32 v170, v170, 9
	v_sub_u32_e32 v137, v137, v170
	v_and_b32_e32 v137, 0xff, v137
	v_lshl_add_u32 v170, v137, 13, v117
	v_add_u32_e32 v174, v170, v116
	v_add_u32_e32 v186, v170, v118
	ds_read_b128 v[170:173], v174
	ds_read_b128 v[174:177], v174 offset:2048
	ds_read_b128 v[194:197], v186
	ds_read_b128 v[198:201], v186 offset:2048
	s_waitcnt lgkmcnt(7)
	v_mfma_f32_16x16x32_bf16 v[162:165], v[162:165], v[92:95], v[24:27]
	s_waitcnt lgkmcnt(6)
	v_mfma_f32_16x16x32_bf16 v[166:169], v[166:169], v[92:95], v[28:31]
	s_waitcnt lgkmcnt(5)
	v_mfma_f32_16x16x32_bf16 v[162:165], v[178:181], v[88:91], v[162:165]
	s_waitcnt lgkmcnt(4)
	v_mfma_f32_16x16x32_bf16 v[166:169], v[182:185], v[88:91], v[166:169]
	s_add_i32 s33, s14, 1
	s_and_b32 s76, s33, 0xff
	s_mul_i32 s76, s76, 57
	s_lshr_b32 s76, s76, 9
	s_mul_i32 s76, s76, 9
	s_sub_i32 s33, s33, s76
	s_and_b32 s86, s33, 0xff
	v_lshl_add_u32 v178, s86, 13, v117
	v_add_u32_e32 v182, v178, v116
	v_add_u32_e32 v186, v178, v118
	ds_read_b128 v[178:181], v182
	ds_read_b128 v[182:185], v182 offset:2048
	ds_read_b128 v[202:205], v186
	ds_read_b128 v[206:209], v186 offset:2048
	s_waitcnt lgkmcnt(7)
	v_mfma_f32_16x16x32_bf16 v[170:173], v[170:173], v[92:95], v[52:55]
	s_waitcnt lgkmcnt(6)
	v_mfma_f32_16x16x32_bf16 v[174:177], v[174:177], v[92:95], v[60:63]
	s_waitcnt lgkmcnt(5)
	v_mfma_f32_16x16x32_bf16 v[170:173], v[194:197], v[88:91], v[170:173]
	s_waitcnt lgkmcnt(4)
	v_mfma_f32_16x16x32_bf16 v[174:177], v[198:201], v[88:91], v[174:177]
	s_add_i32 s33, s14, 2
	s_and_b32 s76, s33, 0xff
	s_mul_i32 s76, s76, 57
	s_lshr_b32 s76, s76, 9
	s_mul_i32 s76, s76, 9
	s_sub_i32 s33, s33, s76
	s_and_b32 s33, s33, 0xff
	v_lshl_add_u32 v186, s33, 13, v117
	v_add_u32_e32 v187, v186, v116
	v_add_u32_e32 v186, v186, v118
	ds_read_b128 v[194:197], v187
	ds_read_b128 v[198:201], v187 offset:2048
	ds_read_b128 v[210:213], v186
	ds_read_b128 v[214:217], v186 offset:2048
	s_waitcnt lgkmcnt(7)
	v_mfma_f32_16x16x32_bf16 v[178:181], v[178:181], v[92:95], v[64:67]
	s_waitcnt lgkmcnt(6)
	v_mfma_f32_16x16x32_bf16 v[182:185], v[182:185], v[92:95], v[68:71]
	s_waitcnt lgkmcnt(5)
	v_mfma_f32_16x16x32_bf16 v[178:181], v[202:205], v[88:91], v[178:181]
	s_waitcnt lgkmcnt(4)
	v_mfma_f32_16x16x32_bf16 v[182:185], v[206:209], v[88:91], v[182:185]
	s_add_i32 s14, s14, 3
	s_and_b32 s76, s14, 0xff
	s_mul_i32 s76, s76, 57
	s_lshr_b32 s76, s76, 9
	s_mul_i32 s76, s76, 9
	s_sub_i32 s14, s14, s76
	s_and_b32 s14, s14, 0xff
	v_lshl_add_u32 v186, s14, 13, v117
	v_add_u32_e32 v187, v186, v116
	v_add_u32_e32 v186, v186, v118
	ds_read_b128 v[202:205], v187
	ds_read_b128 v[206:209], v187 offset:2048
	ds_read_b128 v[218:221], v186
	ds_read_b128 v[222:225], v186 offset:2048
	s_waitcnt lgkmcnt(7)
	v_mfma_f32_16x16x32_bf16 v[194:197], v[194:197], v[92:95], v[72:75]
	s_waitcnt lgkmcnt(6)
	v_mfma_f32_16x16x32_bf16 v[198:201], v[198:201], v[92:95], v[76:79]
	s_waitcnt lgkmcnt(5)
	v_mfma_f32_16x16x32_bf16 v[194:197], v[210:213], v[88:91], v[194:197]
	s_waitcnt lgkmcnt(4)
	v_mfma_f32_16x16x32_bf16 v[198:201], v[214:217], v[88:91], v[198:201]
	s_waitcnt lgkmcnt(3)
	v_mfma_f32_16x16x32_bf16 v[202:205], v[202:205], v[92:95], v[80:83]
	v_cndmask_b32_e64 v142, v138, v142, s[38:39]
	v_cndmask_b32_e64 v143, v139, v143, s[40:41]
	v_cndmask_b32_e64 v144, v140, v144, s[42:43]
	s_waitcnt lgkmcnt(2)
	v_mfma_f32_16x16x32_bf16 v[92:95], v[206:209], v[92:95], v[84:87]
	v_cndmask_b32_e64 v145, v141, v145, s[44:45]
	s_mov_b32 s76, 0xf149f2ca
	v_cndmask_b32_e64 v154, v154, v158, s[38:39]
	s_waitcnt lgkmcnt(1)
	v_mfma_f32_16x16x32_bf16 v[138:141], v[218:221], v[88:91], v[202:205]
	v_cndmask_b32_e64 v155, v155, v159, s[40:41]
	v_cndmask_b32_e64 v156, v156, v160, s[42:43]
	v_cndmask_b32_e64 v157, v157, v161, s[44:45]
	s_waitcnt lgkmcnt(0)
	v_mfma_f32_16x16x32_bf16 v[88:91], v[222:225], v[88:91], v[92:95]
	v_cndmask_b32_e64 v146, v146, v150, s[38:39]
	v_cndmask_b32_e64 v147, v147, v151, s[40:41]
	v_cndmask_b32_e64 v148, v148, v152, s[42:43]
	v_cndmask_b32_e64 v92, v149, v153, s[44:45]
	v_cndmask_b32_e64 v93, v162, v166, s[38:39]
	s_nop 2
	v_cndmask_b32_e64 v88, v138, v88, s[38:39]
	v_max3_f32 v138, v142, s76, v143
	v_max3_f32 v138, v138, v144, v145
	v_max3_f32 v138, v138, v154, v155
	v_max3_f32 v138, v138, v156, v157
	v_max3_f32 v138, v138, v146, v147
	v_cndmask_b32_e64 v94, v163, v167, s[40:41]
	v_max3_f32 v138, v138, v148, v92
	v_cndmask_b32_e64 v95, v164, v168, s[42:43]
	v_cndmask_b32_e64 v149, v165, v169, s[44:45]
	v_max3_f32 v138, v138, v93, v94
	v_cndmask_b32_e64 v150, v170, v174, s[38:39]
	v_cndmask_b32_e64 v151, v171, v175, s[40:41]
	v_max3_f32 v138, v138, v95, v149
	v_cndmask_b32_e64 v152, v172, v176, s[42:43]
	v_cndmask_b32_e64 v153, v173, v177, s[44:45]
	v_max3_f32 v138, v138, v150, v151
	v_cndmask_b32_e64 v158, v178, v182, s[38:39]
	v_cndmask_b32_e64 v159, v179, v183, s[40:41]
	v_max3_f32 v138, v138, v152, v153
	v_cndmask_b32_e64 v160, v180, v184, s[42:43]
	v_cndmask_b32_e64 v161, v181, v185, s[44:45]
	v_max3_f32 v138, v138, v158, v159
	v_cndmask_b32_e64 v162, v194, v198, s[38:39]
	v_cndmask_b32_e64 v163, v195, v199, s[40:41]
	v_cndmask_b32_e64 v90, v140, v90, s[42:43]
	v_max3_f32 v138, v138, v160, v161
	v_and_b32_e32 v140, 64, v228
	v_cndmask_b32_e64 v164, v196, v200, s[42:43]
	v_cndmask_b32_e64 v165, v197, v201, s[44:45]
	v_cndmask_b32_e64 v89, v139, v89, s[40:41]
	v_max3_f32 v138, v138, v162, v163
	v_xor_b32_e32 v139, 16, v228
	v_add_u32_e32 v140, 64, v140
	v_max3_f32 v138, v138, v164, v165
	v_cmp_lt_i32_e32 vcc, v139, v140
	v_cndmask_b32_e64 v91, v141, v91, s[44:45]
	v_max3_f32 v138, v138, v88, v89
	v_cndmask_b32_e32 v139, v228, v139, vcc
	v_max3_f32 v138, v138, v90, v91
	v_lshlrev_b32_e32 v139, 2, v139
	ds_bpermute_b32 v141, v139, v138
	s_waitcnt lgkmcnt(0)
	v_max_f32_e32 v141, v141, v141
	v_max_f32_e32 v138, v138, v141
	v_xor_b32_e32 v141, 32, v228
	v_cmp_lt_i32_e32 vcc, v141, v140
	s_nop 1
	v_cndmask_b32_e32 v140, v228, v141, vcc
	v_lshlrev_b32_e32 v140, 2, v140
	v_mov_b32_e32 v141, v138
	s_nop 1
	v_permlane32_swap_b32_e32 v138, v141
	s_waitcnt lgkmcnt(0)
	v_max_f32_e32 v141, v141, v141
	v_max_f32_e32 v138, v138, v141
	v_sub_f32_e32 v141, v142, v138
	v_exp_f32_e32 v141, v141
	v_sub_f32_e32 v142, v143, v138
	v_exp_f32_e32 v142, v142
	v_sub_f32_e32 v92, v92, v138
	v_add_f32_e32 v143, 0, v141
	v_cndmask_b32_e64 v166, v141, 0, s[38:39]
	v_cndmask_b32_e64 v167, 0, v141, s[38:39]
	v_add_f32_e32 v141, v142, v143
	v_sub_f32_e32 v143, v144, v138
	v_exp_f32_e32 v143, v143
	v_cndmask_b32_e64 v168, v142, 0, s[40:41]
	v_cndmask_b32_e64 v169, 0, v142, s[40:41]
	v_sub_f32_e32 v142, v145, v138
	v_exp_f32_e32 v142, v142
	v_add_f32_e32 v141, v143, v141
	v_cndmask_b32_e64 v170, v143, 0, s[42:43]
	v_cndmask_b32_e64 v171, 0, v143, s[42:43]
	v_sub_f32_e32 v143, v154, v138
	v_exp_f32_e32 v143, v143
	v_add_f32_e32 v141, v142, v141
	v_cndmask_b32_e64 v172, v142, 0, s[44:45]
	v_cndmask_b32_e64 v173, 0, v142, s[44:45]
	v_sub_f32_e32 v142, v155, v138
	v_exp_f32_e32 v142, v142
	v_add_f32_e32 v141, v143, v141
	v_cndmask_b32_e64 v178, v143, 0, s[38:39]
	v_cndmask_b32_e64 v180, 0, v143, s[38:39]
	v_sub_f32_e32 v143, v156, v138
	v_exp_f32_e32 v143, v143
	v_add_f32_e32 v141, v142, v141
	v_cndmask_b32_e64 v179, v142, 0, s[40:41]
	v_cndmask_b32_e64 v181, 0, v142, s[40:41]
	v_sub_f32_e32 v142, v157, v138
	v_exp_f32_e32 v142, v142
	v_add_f32_e32 v141, v143, v141
	v_cndmask_b32_e64 v182, v143, 0, s[42:43]
	v_cndmask_b32_e64 v183, 0, v143, s[42:43]
	v_sub_f32_e32 v143, v146, v138
	v_exp_f32_e32 v143, v143
	v_add_f32_e32 v141, v142, v141
	v_cndmask_b32_e64 v184, v142, 0, s[44:45]
	v_cndmask_b32_e64 v185, 0, v142, s[44:45]
	v_sub_f32_e32 v142, v147, v138
	v_exp_f32_e32 v142, v142
	v_add_f32_e32 v141, v143, v141
	v_cndmask_b32_e64 v186, v143, 0, s[38:39]
	v_cndmask_b32_e64 v187, 0, v143, s[38:39]
	v_sub_f32_e32 v143, v148, v138
	v_exp_f32_e32 v143, v143
	v_exp_f32_e32 v92, v92
	v_add_f32_e32 v141, v142, v141
	v_sub_f32_e32 v93, v93, v138
	v_add_f32_e32 v141, v143, v141
	v_add_f32_e32 v141, v92, v141
	v_cndmask_b32_e64 v196, v92, 0, s[44:45]
	v_exp_f32_e32 v93, v93
	v_cndmask_b32_e64 v197, 0, v92, s[44:45]
	v_sub_f32_e32 v92, v94, v138
	v_exp_f32_e32 v92, v92
	v_add_f32_e32 v94, v93, v141
	v_cndmask_b32_e64 v198, v93, 0, s[38:39]
	v_cndmask_b32_e64 v199, 0, v93, s[38:39]
	v_add_f32_e32 v93, v92, v94
	v_sub_f32_e32 v94, v95, v138
	v_cndmask_b32_e64 v200, v92, 0, s[40:41]
	v_exp_f32_e32 v94, v94
	v_cndmask_b32_e64 v201, 0, v92, s[40:41]
	v_sub_f32_e32 v92, v149, v138
	v_exp_f32_e32 v92, v92
	v_add_f32_e32 v93, v94, v93
	v_cndmask_b32_e64 v202, v94, 0, s[42:43]
	v_cndmask_b32_e64 v203, 0, v94, s[42:43]
	v_sub_f32_e32 v94, v150, v138
	v_add_f32_e32 v93, v92, v93
	v_cndmask_b32_e64 v204, v92, 0, s[44:45]
	v_exp_f32_e32 v94, v94
	v_cndmask_b32_e64 v205, 0, v92, s[44:45]
	v_sub_f32_e32 v92, v151, v138
	v_exp_f32_e32 v92, v92
	v_add_f32_e32 v93, v94, v93
	v_cndmask_b32_e64 v206, v94, 0, s[38:39]
	v_cndmask_b32_e64 v207, 0, v94, s[38:39]
	v_sub_f32_e32 v94, v152, v138
	v_add_f32_e32 v93, v92, v93
	v_cndmask_b32_e64 v208, v92, 0, s[40:41]
	v_exp_f32_e32 v94, v94
	v_cndmask_b32_e64 v209, 0, v92, s[40:41]
	v_sub_f32_e32 v92, v153, v138
	v_exp_f32_e32 v92, v92
	v_add_f32_e32 v93, v94, v93
	v_cndmask_b32_e64 v210, v94, 0, s[42:43]
	v_cndmask_b32_e64 v211, 0, v94, s[42:43]
	v_sub_f32_e32 v94, v158, v138
	v_add_f32_e32 v93, v92, v93
	v_cndmask_b32_e64 v212, v92, 0, s[44:45]
	v_exp_f32_e32 v94, v94
	v_cndmask_b32_e64 v213, 0, v92, s[44:45]
	v_sub_f32_e32 v92, v159, v138
	v_exp_f32_e32 v92, v92
	v_add_f32_e32 v93, v94, v93
	v_cndmask_b32_e64 v214, v94, 0, s[38:39]
	v_cndmask_b32_e64 v215, 0, v94, s[38:39]
	v_sub_f32_e32 v94, v160, v138
	v_add_f32_e32 v93, v92, v93
	v_cndmask_b32_e64 v216, v92, 0, s[40:41]
	v_exp_f32_e32 v94, v94
	v_cndmask_b32_e64 v217, 0, v92, s[40:41]
	v_sub_f32_e32 v92, v161, v138
	v_exp_f32_e32 v92, v92
	v_add_f32_e32 v93, v94, v93
	v_cndmask_b32_e64 v218, v94, 0, s[42:43]
	v_cndmask_b32_e64 v219, 0, v94, s[42:43]
	v_sub_f32_e32 v94, v162, v138
	v_add_f32_e32 v93, v92, v93
	v_cndmask_b32_e64 v220, v92, 0, s[44:45]
	v_exp_f32_e32 v94, v94
	v_cndmask_b32_e64 v221, 0, v92, s[44:45]
	v_sub_f32_e32 v92, v163, v138
	v_exp_f32_e32 v92, v92
	v_add_f32_e32 v93, v94, v93
	v_cndmask_b32_e64 v222, v94, 0, s[38:39]
	v_cndmask_b32_e64 v223, 0, v94, s[38:39]
	v_sub_f32_e32 v94, v164, v138
	v_add_f32_e32 v93, v92, v93
	v_cndmask_b32_e64 v224, v92, 0, s[40:41]
	v_exp_f32_e32 v94, v94
	v_cndmask_b32_e64 v225, 0, v92, s[40:41]
	v_sub_f32_e32 v92, v165, v138
	v_exp_f32_e32 v92, v92
	v_sub_f32_e32 v88, v88, v138
	v_exp_f32_e32 v88, v88
	v_sub_f32_e32 v89, v89, v138
	v_exp_f32_e32 v89, v89
	v_sub_f32_e32 v90, v90, v138
	v_add_f32_e32 v93, v94, v93
	v_exp_f32_e32 v146, v90
	v_sub_f32_e32 v90, v91, v138
	v_add_f32_e32 v93, v92, v93
	v_exp_f32_e32 v147, v90
	v_add_f32_e32 v90, v88, v93
	v_add_f32_e32 v90, v89, v90
	v_add_f32_e32 v90, v146, v90
	v_add_f32_e32 v90, v147, v90
	ds_bpermute_b32 v91, v139, v90
	v_cndmask_b32_e64 v188, v142, 0, s[40:41]
	v_cndmask_b32_e64 v193, 0, v142, s[40:41]
	v_lshl_add_u32 v142, s92, 7, v119
	v_cndmask_b32_e64 v234, v92, 0, s[44:45]
	v_cndmask_b32_e64 v235, 0, v92, s[44:45]
	v_cndmask_b32_e64 v236, v88, 0, s[38:39]
	v_cndmask_b32_e64 v237, 0, v88, s[38:39]
	v_cndmask_b32_e64 v238, v89, 0, s[40:41]
	v_cndmask_b32_e64 v239, 0, v89, s[40:41]
	s_waitcnt lgkmcnt(0)
	v_add_f32_e32 v240, v90, v91
	ds_read2_b64 v[88:91], v142 offset1:4
	v_add_u32_e32 v92, 0x4800, v142
	v_add_u32_e32 v138, 0x9000, v142
	v_add_u32_e32 v142, 0xd800, v142
	v_cndmask_b32_e64 v194, v143, 0, s[42:43]
	v_cndmask_b32_e64 v195, 0, v143, s[42:43]
	v_cndmask_b32_e64 v226, v94, 0, s[42:43]
	v_cndmask_b32_e64 v227, 0, v94, s[42:43]
	ds_bpermute_b32 v241, v140, v240
	ds_read2_b64 v[92:95], v92 offset0:32 offset1:36
	ds_read2_b64 v[138:141], v138 offset0:64 offset1:68
	ds_read2_b64 v[142:145], v142 offset0:96 offset1:100
	v_cndmask_b32_e64 v242, v146, 0, s[42:43]
	v_cndmask_b32_e64 v243, 0, v146, s[42:43]
	v_cndmask_b32_e64 v244, v147, 0, s[44:45]
	v_cndmask_b32_e64 v245, 0, v147, s[44:45]
	v_lshl_add_u32 v158, s91, 7, v119
	ds_read2_b64 v[146:149], v158 offset1:4
	v_add_u32_e32 v150, 0x4800, v158
	v_add_u32_e32 v154, 0x9000, v158
	v_add_u32_e32 v158, 0xd800, v158
	ds_read2_b64 v[150:153], v150 offset0:32 offset1:36
	ds_read2_b64 v[154:157], v154 offset0:64 offset1:68
	ds_read2_b64 v[158:161], v158 offset0:96 offset1:100
	v_cvt_pk_bf16_f32 v162, v166, v168
	v_cvt_pk_bf16_f32 v163, v170, v172
	v_cvt_pk_bf16_f32 v164, v167, v169
	v_cvt_pk_bf16_f32 v165, v171, v173
	s_waitcnt lgkmcnt(8)
	s_nop 0
	v_mfma_f32_16x16x32_bf16 v[88:91], v[88:91], v[162:165], 0
	s_waitcnt lgkmcnt(6)
	v_mfma_f32_16x16x32_bf16 v[92:95], v[92:95], v[162:165], 0
	s_waitcnt lgkmcnt(5)
	v_mfma_f32_16x16x32_bf16 v[138:141], v[138:141], v[162:165], 0
	s_waitcnt lgkmcnt(4)
	v_mfma_f32_16x16x32_bf16 v[142:145], v[142:145], v[162:165], 0
	v_lshl_add_u32 v174, s90, 7, v119
	ds_read2_b64 v[162:165], v174 offset1:4
	v_add_u32_e32 v166, 0x4800, v174
	v_add_u32_e32 v170, 0x9000, v174
	v_add_u32_e32 v174, 0xd800, v174
	ds_read2_b64 v[166:169], v166 offset0:32 offset1:36
	ds_read2_b64 v[170:173], v170 offset0:64 offset1:68
	ds_read2_b64 v[174:177], v174 offset0:96 offset1:100
	v_cvt_pk_bf16_f32 v178, v178, v179
	v_cvt_pk_bf16_f32 v179, v182, v184
	v_cvt_pk_bf16_f32 v180, v180, v181
	v_cvt_pk_bf16_f32 v181, v183, v185
	s_waitcnt lgkmcnt(7)
	s_nop 0
	v_mfma_f32_16x16x32_bf16 v[88:91], v[146:149], v[178:181], v[88:91]
	s_waitcnt lgkmcnt(6)
	v_mfma_f32_16x16x32_bf16 v[92:95], v[150:153], v[178:181], v[92:95]
	s_waitcnt lgkmcnt(5)
	v_mfma_f32_16x16x32_bf16 v[138:141], v[154:157], v[178:181], v[138:141]
	s_waitcnt lgkmcnt(4)
	v_mfma_f32_16x16x32_bf16 v[142:145], v[158:161], v[178:181], v[142:145]
	v_lshl_add_u32 v158, s87, 7, v119
	ds_read2_b64 v[146:149], v158 offset1:4
	v_add_u32_e32 v150, 0x4800, v158
	v_add_u32_e32 v154, 0x9000, v158
	v_add_u32_e32 v158, 0xd800, v158
	ds_read2_b64 v[150:153], v150 offset0:32 offset1:36
	ds_read2_b64 v[154:157], v154 offset0:64 offset1:68
	ds_read2_b64 v[158:161], v158 offset0:96 offset1:100
	v_cvt_pk_bf16_f32 v178, v186, v188
	v_cvt_pk_bf16_f32 v179, v194, v196
	v_cvt_pk_bf16_f32 v180, v187, v193
	v_cvt_pk_bf16_f32 v181, v195, v197
	s_waitcnt lgkmcnt(7)
	s_nop 0
	v_mfma_f32_16x16x32_bf16 v[88:91], v[162:165], v[178:181], v[88:91]
	s_waitcnt lgkmcnt(6)
	v_mfma_f32_16x16x32_bf16 v[92:95], v[166:169], v[178:181], v[92:95]
	s_waitcnt lgkmcnt(5)
	v_mfma_f32_16x16x32_bf16 v[138:141], v[170:173], v[178:181], v[138:141]
	s_waitcnt lgkmcnt(4)
	v_mfma_f32_16x16x32_bf16 v[142:145], v[174:177], v[178:181], v[142:145]
	v_lshl_add_u32 v137, v137, 7, v119
	ds_read2_b64 v[162:165], v137 offset1:4
	v_add_u32_e32 v166, 0x4800, v137
	v_add_u32_e32 v170, 0x9000, v137
	v_add_u32_e32 v137, 0xd800, v137
	ds_read2_b64 v[166:169], v166 offset0:32 offset1:36
	ds_read2_b64 v[170:173], v170 offset0:64 offset1:68
	ds_read2_b64 v[174:177], v137 offset0:96 offset1:100
	v_cvt_pk_bf16_f32 v178, v198, v200
	v_cvt_pk_bf16_f32 v179, v202, v204
	v_cvt_pk_bf16_f32 v180, v199, v201
	v_cvt_pk_bf16_f32 v181, v203, v205
	s_waitcnt lgkmcnt(7)
	s_nop 0
	v_mfma_f32_16x16x32_bf16 v[88:91], v[146:149], v[178:181], v[88:91]
	s_waitcnt lgkmcnt(6)
	v_mfma_f32_16x16x32_bf16 v[92:95], v[150:153], v[178:181], v[92:95]
	s_waitcnt lgkmcnt(5)
	v_mfma_f32_16x16x32_bf16 v[138:141], v[154:157], v[178:181], v[138:141]
	s_waitcnt lgkmcnt(4)
	v_mfma_f32_16x16x32_bf16 v[142:145], v[158:161], v[178:181], v[142:145]
	v_lshl_add_u32 v137, s86, 7, v119
	ds_read2_b64 v[146:149], v137 offset1:4
	v_add_u32_e32 v150, 0x4800, v137
	v_add_u32_e32 v154, 0x9000, v137
	v_add_u32_e32 v137, 0xd800, v137
	ds_read2_b64 v[150:153], v150 offset0:32 offset1:36
	ds_read2_b64 v[154:157], v154 offset0:64 offset1:68
	ds_read2_b64 v[158:161], v137 offset0:96 offset1:100
	v_cvt_pk_bf16_f32 v178, v206, v208
	v_cvt_pk_bf16_f32 v179, v210, v212
	v_cvt_pk_bf16_f32 v180, v207, v209
	v_cvt_pk_bf16_f32 v181, v211, v213
	s_waitcnt lgkmcnt(7)
	s_nop 0
	v_mfma_f32_16x16x32_bf16 v[88:91], v[162:165], v[178:181], v[88:91]
	s_waitcnt lgkmcnt(6)
	v_mfma_f32_16x16x32_bf16 v[92:95], v[166:169], v[178:181], v[92:95]
	s_waitcnt lgkmcnt(5)
	v_mfma_f32_16x16x32_bf16 v[138:141], v[170:173], v[178:181], v[138:141]
	s_waitcnt lgkmcnt(4)
	v_mfma_f32_16x16x32_bf16 v[142:145], v[174:177], v[178:181], v[142:145]
	v_lshl_add_u32 v137, s33, 7, v119
	ds_read2_b64 v[162:165], v137 offset1:4
	v_add_u32_e32 v166, 0x4800, v137
	v_add_u32_e32 v170, 0x9000, v137
	v_add_u32_e32 v137, 0xd800, v137
	ds_read2_b64 v[166:169], v166 offset0:32 offset1:36
	ds_read2_b64 v[170:173], v170 offset0:64 offset1:68
	ds_read2_b64 v[174:177], v137 offset0:96 offset1:100
	v_cvt_pk_bf16_f32 v178, v214, v216
	v_cvt_pk_bf16_f32 v179, v218, v220
	v_cvt_pk_bf16_f32 v180, v215, v217
	v_cvt_pk_bf16_f32 v181, v219, v221
	s_waitcnt lgkmcnt(7)
	s_nop 0
	v_mfma_f32_16x16x32_bf16 v[88:91], v[146:149], v[178:181], v[88:91]
	s_waitcnt lgkmcnt(6)
	v_mfma_f32_16x16x32_bf16 v[92:95], v[150:153], v[178:181], v[92:95]
	s_waitcnt lgkmcnt(5)
	v_mfma_f32_16x16x32_bf16 v[138:141], v[154:157], v[178:181], v[138:141]
	s_waitcnt lgkmcnt(4)
	v_mfma_f32_16x16x32_bf16 v[142:145], v[158:161], v[178:181], v[142:145]
	v_lshl_add_u32 v137, s14, 7, v119
	ds_read2_b64 v[146:149], v137 offset1:4
	v_add_u32_e32 v150, 0x4800, v137
	v_add_u32_e32 v154, 0x9000, v137
	v_add_u32_e32 v137, 0xd800, v137
	ds_read2_b64 v[150:153], v150 offset0:32 offset1:36
	ds_read2_b64 v[154:157], v154 offset0:64 offset1:68
	ds_read2_b64 v[158:161], v137 offset0:96 offset1:100
	v_cvt_pk_bf16_f32 v178, v222, v224
	v_cvt_pk_bf16_f32 v179, v226, v234
	v_cvt_pk_bf16_f32 v180, v223, v225
	v_cvt_pk_bf16_f32 v181, v227, v235
	s_waitcnt lgkmcnt(7)
	s_nop 0
	v_mfma_f32_16x16x32_bf16 v[88:91], v[162:165], v[178:181], v[88:91]
	s_waitcnt lgkmcnt(6)
	v_mfma_f32_16x16x32_bf16 v[92:95], v[166:169], v[178:181], v[92:95]
	s_waitcnt lgkmcnt(5)
	v_mfma_f32_16x16x32_bf16 v[138:141], v[170:173], v[178:181], v[138:141]
	s_waitcnt lgkmcnt(4)
	v_mfma_f32_16x16x32_bf16 v[142:145], v[174:177], v[178:181], v[142:145]
	v_cvt_pk_bf16_f32 v162, v236, v238
	v_cvt_pk_bf16_f32 v163, v242, v244
	v_cvt_pk_bf16_f32 v164, v237, v239
	v_cvt_pk_bf16_f32 v165, v243, v245
	v_add_f32_e32 v137, v240, v241
	s_brev_b32 s14, 47
	s_waitcnt lgkmcnt(3)
	v_mfma_f32_16x16x32_bf16 v[88:91], v[146:149], v[162:165], v[88:91]
	s_waitcnt vmcnt(3)
	v_lshlrev_b32_e32 v146, 16, v112
	v_mul_f32_e32 v147, 0xbfb8aa3b, v146
	v_exp_f32_e32 v149, v147
	v_and_b32_e32 v147, 0xffff0000, v112
	v_rcp_f32_e32 v148, v137
	v_mul_f32_e32 v137, 0xbfb8aa3b, v147
	v_exp_f32_e32 v137, v137
	v_add_f32_e32 v112, 1.0, v149
	s_waitcnt lgkmcnt(2)
	v_mfma_f32_16x16x32_bf16 v[92:95], v[150:153], v[162:165], v[92:95]
	v_rcp_f32_e32 v150, v112
	v_add_f32_e32 v112, 1.0, v137
	v_rcp_f32_e32 v151, v112
	v_lshlrev_b32_e32 v112, 16, v113
	v_pk_mul_f32 v[88:89], v[148:149], v[88:89] op_sel_hi:[0,1]
	v_and_b32_e32 v113, 0xffff0000, v113
	v_mul_f32_e32 v137, 0xbfb8aa3b, v112
	v_pk_mul_f32 v[88:89], v[88:89], v[146:147]
	v_exp_f32_e32 v137, v137
	v_mul_f32_e32 v146, 0xbfb8aa3b, v113
	v_exp_f32_e32 v147, v146
	v_pk_mul_f32 v[90:91], v[148:149], v[90:91] op_sel_hi:[0,1]
	v_add_f32_e32 v137, 1.0, v137
	v_rcp_f32_e32 v146, v137
	v_add_f32_e32 v137, 1.0, v147
	v_rcp_f32_e32 v147, v137
	v_pk_mul_f32 v[90:91], v[90:91], v[112:113]
	v_pk_mul_f32 v[88:89], v[150:151], v[88:89]
	v_add_co_u32_e32 v112, vcc, s14, v104
	v_pk_mul_f32 v[90:91], v[146:147], v[90:91]
	v_cvt_pk_bf16_f32 v88, v88, v89
	v_cvt_pk_bf16_f32 v89, v90, v91
	s_waitcnt vmcnt(2)
	v_lshlrev_b32_e32 v90, 16, v110
	v_mul_f32_e32 v91, 0xbfb8aa3b, v90
	v_exp_f32_e32 v137, v91
	v_addc_co_u32_e32 v113, vcc, -1, v105, vcc
	v_and_b32_e32 v91, 0xffff0000, v110
	global_store_dwordx2 v[112:113], v[88:89], off offset:-96
	v_mul_f32_e32 v89, 0xbfb8aa3b, v91
	v_exp_f32_e32 v89, v89
	v_pk_mul_f32 v[92:93], v[148:149], v[92:93] op_sel_hi:[0,1]
	v_pk_mul_f32 v[90:91], v[92:93], v[90:91]
	v_lshlrev_b32_e32 v92, 16, v111
	v_and_b32_e32 v93, 0xffff0000, v111
	v_add_f32_e32 v88, 1.0, v137
	v_add_f32_e32 v89, 1.0, v89
	v_mul_f32_e32 v110, 0xbfb8aa3b, v92
	v_mul_f32_e32 v111, 0xbfb8aa3b, v93
	v_rcp_f32_e32 v88, v88
	v_rcp_f32_e32 v89, v89
	v_exp_f32_e32 v110, v110
	v_exp_f32_e32 v111, v111
	v_pk_mul_f32 v[94:95], v[148:149], v[94:95] op_sel_hi:[0,1]
	v_pk_mul_f32 v[88:89], v[88:89], v[90:91]
	v_add_f32_e32 v90, 1.0, v110
	v_add_f32_e32 v91, 1.0, v111
	v_rcp_f32_e32 v90, v90
	v_rcp_f32_e32 v91, v91
	v_pk_mul_f32 v[92:93], v[94:95], v[92:93]
	v_cvt_pk_bf16_f32 v88, v88, v89
	s_waitcnt lgkmcnt(1)
	v_mfma_f32_16x16x32_bf16 v[138:141], v[154:157], v[162:165], v[138:141]
	v_mul_f32_e64 v90, v90, v92
	v_mul_f32_e64 v91, v91, v93
	s_waitcnt vmcnt(2)
	v_lshlrev_b32_e32 v92, 16, v108
	v_mul_f32_e32 v89, 0xbfb8aa3b, v92
	v_exp_f32_e32 v94, v89
	v_cvt_pk_bf16_f32 v89, v90, v91
	v_and_b32_e32 v93, 0xffff0000, v108
	global_store_dwordx2 v[112:113], v[88:89], off offset:-64
	v_mul_f32_e32 v89, 0xbfb8aa3b, v93
	v_exp_f32_e32 v89, v89
	v_pk_mul_f32 v[90:91], v[148:149], v[138:139] op_sel_hi:[0,1]
	v_pk_mul_f32 v[90:91], v[90:91], v[92:93]
	v_lshlrev_b32_e32 v92, 16, v109
	v_and_b32_e32 v93, 0xffff0000, v109
	v_add_f32_e32 v88, 1.0, v94
	v_add_f32_e32 v89, 1.0, v89
	v_mul_f32_e32 v94, 0xbfb8aa3b, v92
	v_mul_f32_e32 v95, 0xbfb8aa3b, v93
	v_rcp_f32_e32 v88, v88
	v_rcp_f32_e32 v89, v89
	v_exp_f32_e32 v94, v94
	v_exp_f32_e32 v95, v95
	s_waitcnt lgkmcnt(0)
	v_mfma_f32_16x16x32_bf16 v[142:145], v[158:161], v[162:165], v[142:145]
	v_mul_f32_e64 v88, v88, v90
	v_mul_f32_e64 v89, v89, v91
	v_add_f32_e32 v90, 1.0, v94
	v_add_f32_e32 v91, 1.0, v95
	v_rcp_f32_e32 v90, v90
	v_rcp_f32_e32 v91, v91
	v_pk_mul_f32 v[94:95], v[148:149], v[140:141] op_sel_hi:[0,1]
	v_pk_mul_f32 v[92:93], v[94:95], v[92:93]
	v_cvt_pk_bf16_f32 v88, v88, v89
	v_pk_mul_f32 v[90:91], v[90:91], v[92:93]
	s_waitcnt vmcnt(2)
	v_lshlrev_b32_e32 v92, 16, v106
	v_mul_f32_e32 v89, 0xbfb8aa3b, v92
	v_exp_f32_e32 v94, v89
	v_cvt_pk_bf16_f32 v89, v90, v91
	v_and_b32_e32 v93, 0xffff0000, v106
	global_store_dwordx2 v[112:113], v[88:89], off offset:-32
	v_mul_f32_e32 v89, 0xbfb8aa3b, v93
	v_exp_f32_e32 v89, v89
	v_pk_mul_f32 v[90:91], v[148:149], v[142:143] op_sel_hi:[0,1]
	v_pk_mul_f32 v[90:91], v[90:91], v[92:93]
	v_lshlrev_b32_e32 v92, 16, v107
	v_and_b32_e32 v93, 0xffff0000, v107
	v_add_f32_e32 v88, 1.0, v94
	v_add_f32_e32 v89, 1.0, v89
	v_mul_f32_e32 v94, 0xbfb8aa3b, v92
	v_mul_f32_e32 v95, 0xbfb8aa3b, v93
	v_rcp_f32_e32 v88, v88
	v_rcp_f32_e32 v89, v89
	v_exp_f32_e32 v94, v94
	v_exp_f32_e32 v95, v95
	s_andn2_b64 vcc, exec, s[18:19]
	v_pk_mul_f32 v[88:89], v[88:89], v[90:91]
	v_add_f32_e32 v90, 1.0, v94
	v_add_f32_e32 v91, 1.0, v95
	v_rcp_f32_e32 v90, v90
	v_rcp_f32_e32 v91, v91
	v_pk_mul_f32 v[94:95], v[148:149], v[144:145] op_sel_hi:[0,1]
	v_pk_mul_f32 v[92:93], v[94:95], v[92:93]
	v_cvt_pk_bf16_f32 v88, v88, v89
	v_pk_mul_f32 v[90:91], v[90:91], v[92:93]
	s_nop 0
	v_cvt_pk_bf16_f32 v89, v90, v91
	global_store_dwordx2 v[112:113], v[88:89], off
	s_waitcnt lgkmcnt(0)
	s_barrier
	s_cbranch_vccnz .LBB0_165
	s_mul_i32 s14, s85, 57
	s_lshr_b32 s14, s14, 9
	s_mul_i32 s14, s14, 9
	s_sub_i32 s14, s85, s14
	s_and_b32 s14, s14, 0xff
	v_lshl_add_u32 v88, s14, 13, v114
	ds_write_b128 v88, v[48:51]
	v_lshl_add_u32 v48, s14, 7, v115
	ds_write_b128 v48, v[56:59]
.LBB0_165:
	s_cmp_lt_u32 s83, 13
	s_cselect_b64 s[18:19], -1, 0
	s_and_b64 s[18:19], s[60:61], s[18:19]
	s_andn2_b64 vcc, exec, s[18:19]
	s_cbranch_vccnz .LBB0_160
	s_mul_i32 s14, s84, 57
	s_lshr_b32 s14, s14, 9
	s_mul_i32 s14, s14, 9
	s_sub_i32 s14, s84, s14
	s_and_b32 s14, s14, 0xff
	v_lshl_add_u32 v48, s14, 13, v114
	ds_write_b128 v48, v[32:35]
	v_lshl_add_u32 v32, s14, 7, v115
	ds_write_b128 v32, v[44:47]
	s_branch .LBB0_160
	s_nop 0
	s_nop 0
	s_nop 0
	s_nop 0
	s_nop 0
	s_nop 0
	s_nop 0
	s_nop 0
	s_nop 0
	s_nop 0
	s_nop 0
	s_nop 0
	s_nop 0
	s_nop 0
	s_nop 0
